# GEMM phases: one static s_setprio 1 for the lagging wave half (waves 4-7) before the K loop instead of per-cluster flips
# speedup vs baseline: 1.0208x; 1.0007x over previous
.LBB0_87:
	s_andn2_b64 vcc, exec, s[0:1]
	s_cbranch_vccnz .LBB0_120
	v_readlane_b32 s0, v253, 29
	v_mov_b32_e32 v6, v179
	v_readlane_b32 s1, v253, 30
	s_andn2_b64 vcc, exec, s[0:1]
	v_readfirstlane_b32 s92, v6
	s_cbranch_vccnz .LBB0_120
	v_lshlrev_b32_e32 v3, 4, v6
	v_add_u32_e32 v1, 0x2000, v3
	v_ashrrev_i32_e32 v0, 31, v1
	v_lshrrev_b32_e32 v0, 22, v0
	v_add_u32_e32 v0, v1, v0
	v_ashrrev_i32_e32 v0, 10, v0
	v_mul_i32_i24_e32 v2, 0x400, v0
	v_sub_u32_e32 v1, v1, v2
	v_lshrrev_b32_e32 v2, 4, v1
	v_bitop3_b32 v2, v2, v1, 32 bitop3:0x6c
	v_ashrrev_i32_e32 v1, 31, v2
	v_lshrrev_b32_e32 v1, 26, v1
	v_add_u32_e32 v4, v2, v1
	v_lshlrev_b32_e32 v5, 3, v0
	v_ashrrev_i32_e32 v1, 6, v4
	v_and_b32_e32 v5, -16, v5
	v_add_u32_e32 v5, v1, v5
	v_and_b32_e32 v7, 3, v1
	s_mov_b32 s1, 0x7ffe0
	s_waitcnt vmcnt(0)
	v_lshrrev_b32_e32 v8, 2, v5
	v_lshlrev_b32_e32 v9, 1, v5
	v_and_b32_e32 v4, 0xc0, v4
	v_and_or_b32 v7, v5, s1, v7
	v_and_b32_e32 v8, 4, v8
	v_and_b32_e32 v9, 24, v9
	v_sub_u32_e32 v2, v2, v4
	v_or3_b32 v7, v7, v8, v9
	v_lshlrev_b32_e32 v8, 5, v0
	v_ashrrev_i16_sdwa v2, v181, sext(v2) dst_sel:DWORD dst_unused:UNUSED_PAD src0_sel:DWORD src1_sel:BYTE_0
	v_and_b32_e32 v8, 32, v8
	v_bfe_i32 v2, v2, 0, 16
	v_add_lshl_u32 v4, v8, v2, 1
	v_lshl_add_u32 v152, v7, 13, v4
	v_lshl_add_u32 v154, v5, 13, v4
	v_bfe_i32 v4, v6, 27, 1
	v_lshrrev_b32_e32 v4, 22, v4
	v_add_u32_e32 v4, v3, v4
	v_and_b32_e32 v4, 0xfffffc00, v4
	v_sub_u32_e32 v3, v3, v4
	v_lshrrev_b32_e32 v4, 4, v3
	v_bitop3_b32 v5, v4, v3, 32 bitop3:0x6c
	v_ashrrev_i32_e32 v4, 31, v6
	v_lshrrev_b32_e32 v4, 26, v4
	v_ashrrev_i32_e32 v3, 31, v3
	v_add_u32_e32 v4, v6, v4
	v_lshrrev_b32_e32 v3, 26, v3
	v_ashrrev_i32_e32 v4, 6, v4
	v_add_u32_e32 v3, v5, v3
	v_lshlrev_b32_e32 v7, 3, v4
	v_ashrrev_i32_e32 v3, 6, v3
	v_and_b32_e32 v7, -16, v7
	v_add_u32_e32 v7, v3, v7
	v_and_b32_e32 v8, 3, v3
	v_lshrrev_b32_e32 v9, 2, v7
	v_lshlrev_b32_e32 v10, 1, v7
	v_and_or_b32 v8, v7, s1, v8
	v_and_b32_e32 v9, 4, v9
	v_and_b32_e32 v10, 24, v10
	v_or3_b32 v8, v8, v9, v10
	v_mul_i32_i24_e32 v10, 64, v3
	v_sub_u32_e32 v5, v5, v10
	s_ashr_i32 s0, s92, 6
	v_lshlrev_b32_e32 v9, 5, v4
	v_ashrrev_i16_sdwa v5, v181, sext(v5) dst_sel:DWORD dst_unused:UNUSED_PAD src0_sel:DWORD src1_sel:BYTE_0
	s_lshl_b32 s54, s0, 10
	v_and_b32_e32 v9, 32, v9
	v_bfe_i32 v5, v5, 0, 16
	v_add_lshl_u32 v9, v9, v5, 1
	s_add_i32 s55, s54, 0
	v_readlane_b32 s2, v254, 35
	v_lshl_add_u32 v176, v8, 13, v9
	s_add_i32 m0, s55, 0x10000
	v_readlane_b32 s3, v254, 36
	v_lshl_add_u32 v156, v7, 13, v9
	s_add_i32 s56, s55, 0x2000
	s_add_i32 s57, s55, 0x4000
	s_add_i32 s58, s55, 0x6000
	s_load_dword s59, s[74:75], 0x0
	global_load_lds_dwordx4 v176, s[2:3]
	s_add_i32 m0, s55, 0x12000
	s_ashr_i32 s1, s92, 8
	global_load_lds_dwordx4 v152, s[2:3]
	v_readlane_b32 s2, v254, 31
	s_mov_b32 m0, s55
	v_readlane_b32 s3, v254, 32
	s_nop 4
	global_load_lds_dwordx4 v156, s[2:3]
	s_mov_b32 m0, s56
	s_nop 0
	global_load_lds_dwordx4 v154, s[2:3]
	v_readlane_b32 s2, v254, 29
	s_add_i32 m0, s55, 0x14000
	v_readlane_b32 s3, v254, 30
	s_nop 4
	global_load_lds_dwordx4 v176, s[2:3]
	s_add_i32 m0, s55, 0x16000
	s_cmp_lg_u32 s1, 1
	global_load_lds_dwordx4 v152, s[2:3]
	v_readlane_b32 s2, v254, 33
	s_mov_b32 m0, s57
	v_readlane_b32 s3, v254, 34
	s_nop 4
	global_load_lds_dwordx4 v156, s[2:3]
	s_mov_b32 m0, s58
	s_nop 0
	global_load_lds_dwordx4 v154, s[2:3]
	s_cbranch_scc1 .LBB0_91
	s_barrier
	s_setprio 1

.LBB0_119:
	s_barrier
	s_setprio 0

.LBB0_135:
	s_or_b64 exec, exec, s[0:1]
	v_readlane_b32 s0, v253, 33
	v_mov_b32_e32 v6, v179
	v_readlane_b32 s1, v253, 34
	s_waitcnt lgkmcnt(0)
	s_barrier
	s_andn2_b64 vcc, exec, s[0:1]
	v_readfirstlane_b32 s92, v6
	s_cbranch_vccnz .LBB0_155
	v_lshlrev_b32_e32 v3, 4, v6
	v_add_u32_e32 v1, 0x2000, v3
	v_ashrrev_i32_e32 v0, 31, v1
	v_lshrrev_b32_e32 v0, 22, v0
	v_add_u32_e32 v0, v1, v0
	v_ashrrev_i32_e32 v0, 10, v0
	v_mul_i32_i24_e32 v2, 0x400, v0
	v_sub_u32_e32 v1, v1, v2
	v_lshrrev_b32_e32 v2, 4, v1
	v_bitop3_b32 v2, v2, v1, 32 bitop3:0x6c
	v_ashrrev_i32_e32 v1, 31, v2
	v_lshrrev_b32_e32 v1, 26, v1
	v_add_u32_e32 v4, v2, v1
	v_lshlrev_b32_e32 v5, 3, v0
	v_ashrrev_i32_e32 v1, 6, v4
	v_and_b32_e32 v5, -16, v5
	v_add_u32_e32 v5, v1, v5
	v_and_b32_e32 v7, 3, v1
	s_mov_b32 s0, 0x1fffe0
	s_waitcnt vmcnt(0)
	v_lshrrev_b32_e32 v8, 2, v5
	v_lshlrev_b32_e32 v9, 1, v5
	v_and_b32_e32 v4, 0xc0, v4
	v_and_or_b32 v7, v5, s0, v7
	v_and_b32_e32 v8, 4, v8
	v_and_b32_e32 v9, 24, v9
	v_sub_u32_e32 v2, v2, v4
	v_or3_b32 v7, v7, v8, v9
	v_lshlrev_b32_e32 v8, 5, v0
	v_ashrrev_i16_sdwa v2, v181, sext(v2) dst_sel:DWORD dst_unused:UNUSED_PAD src0_sel:DWORD src1_sel:BYTE_0
	v_and_b32_e32 v8, 32, v8
	v_bfe_i32 v2, v2, 0, 16
	v_add_lshl_u32 v4, v8, v2, 1
	v_lshl_add_u32 v144, v7, 11, v4
	v_lshl_add_u32 v146, v5, 11, v4
	v_bfe_i32 v4, v6, 27, 1
	v_lshrrev_b32_e32 v4, 22, v4
	v_add_u32_e32 v4, v3, v4
	v_and_b32_e32 v4, 0xfffffc00, v4
	v_sub_u32_e32 v3, v3, v4
	v_lshrrev_b32_e32 v4, 4, v3
	v_bitop3_b32 v5, v4, v3, 32 bitop3:0x6c
	v_ashrrev_i32_e32 v4, 31, v6
	v_lshrrev_b32_e32 v4, 26, v4
	v_ashrrev_i32_e32 v3, 31, v3
	v_add_u32_e32 v4, v6, v4
	v_lshrrev_b32_e32 v3, 26, v3
	v_ashrrev_i32_e32 v4, 6, v4
	v_add_u32_e32 v3, v5, v3
	v_lshlrev_b32_e32 v7, 3, v4
	v_ashrrev_i32_e32 v3, 6, v3
	v_and_b32_e32 v7, -16, v7
	v_add_u32_e32 v7, v3, v7
	v_and_b32_e32 v8, 3, v3
	v_lshrrev_b32_e32 v9, 2, v7
	v_lshlrev_b32_e32 v10, 1, v7
	v_and_or_b32 v8, v7, s0, v8
	v_and_b32_e32 v9, 4, v9
	v_and_b32_e32 v10, 24, v10
	v_or3_b32 v8, v8, v9, v10
	v_mul_i32_i24_e32 v10, 64, v3
	v_sub_u32_e32 v5, v5, v10
	s_ashr_i32 s1, s92, 6
	v_lshlrev_b32_e32 v9, 5, v4
	v_ashrrev_i16_sdwa v5, v181, sext(v5) dst_sel:DWORD dst_unused:UNUSED_PAD src0_sel:DWORD src1_sel:BYTE_0
	s_lshl_b32 s56, s1, 10
	v_and_b32_e32 v9, 32, v9
	v_bfe_i32 v5, v5, 0, 16
	v_add_lshl_u32 v9, v9, v5, 1
	s_add_i32 s57, s56, 0
	v_readlane_b32 s2, v254, 6
	v_lshl_add_u32 v176, v8, 11, v9
	s_add_i32 m0, s57, 0x10000
	v_readlane_b32 s3, v254, 7
	v_lshl_add_u32 v148, v7, 11, v9
	s_add_i32 s58, s57, 0x2000
	s_add_i32 s7, s57, 0x4000
	s_add_i32 s15, s57, 0x6000
	s_ashr_i32 s0, s92, 8
	global_load_lds_dwordx4 v176, s[2:3]
	s_add_i32 m0, s57, 0x12000
	s_nop 0
	global_load_lds_dwordx4 v144, s[2:3]
	v_readlane_b32 s2, v254, 2
	s_mov_b32 m0, s57
	v_readlane_b32 s3, v254, 3
	s_nop 4
	global_load_lds_dwordx4 v148, s[2:3]
	s_mov_b32 m0, s58
	s_nop 0
	global_load_lds_dwordx4 v146, s[2:3]
	v_readlane_b32 s2, v254, 0
	s_add_i32 m0, s57, 0x14000
	v_readlane_b32 s3, v254, 1
	s_nop 4
	global_load_lds_dwordx4 v176, s[2:3]
	s_add_i32 m0, s57, 0x16000
	s_cmp_lg_u32 s0, 1
	global_load_lds_dwordx4 v144, s[2:3]
	v_readlane_b32 s2, v254, 4
	s_mov_b32 m0, s7
	v_readlane_b32 s3, v254, 5
	s_nop 4
	global_load_lds_dwordx4 v148, s[2:3]
	s_mov_b32 m0, s15
	s_nop 0
	global_load_lds_dwordx4 v146, s[2:3]
	s_cbranch_scc1 .LBB0_138
	s_barrier
	s_setprio 1

.LBB0_156:
	s_and_b64 vcc, exec, s[0:1]
	s_cbranch_vccz .LBB0_191
	v_readlane_b32 s0, v255, 25
	s_cmp_eq_u32 s0, 4
	s_cbranch_scc0 .LBB0_190
	v_readlane_b32 s0, v253, 29
	v_mov_b32_e32 v6, v179
	v_readlane_b32 s1, v253, 30
	s_andn2_b64 vcc, exec, s[0:1]
	v_readfirstlane_b32 s94, v6
	s_cbranch_vccnz .LBB0_190
	v_lshlrev_b32_e32 v3, 4, v6
	s_waitcnt lgkmcnt(0)
	v_add_u32_e32 v1, 0x2000, v3
	v_ashrrev_i32_e32 v0, 31, v1
	v_lshrrev_b32_e32 v0, 22, v0
	v_add_u32_e32 v0, v1, v0
	v_ashrrev_i32_e32 v0, 10, v0
	v_mul_i32_i24_e32 v2, 0x400, v0
	v_sub_u32_e32 v1, v1, v2
	v_lshrrev_b32_e32 v2, 4, v1
	v_bitop3_b32 v2, v2, v1, 32 bitop3:0x6c
	v_ashrrev_i32_e32 v1, 31, v2
	v_lshrrev_b32_e32 v1, 26, v1
	v_add_u32_e32 v4, v2, v1
	v_lshlrev_b32_e32 v5, 3, v0
	v_ashrrev_i32_e32 v1, 6, v4
	v_and_b32_e32 v5, -16, v5
	v_add_u32_e32 v5, v1, v5
	v_and_b32_e32 v7, 3, v1
	s_mov_b32 s1, 0x1fffe0
	s_waitcnt vmcnt(0)
	v_lshrrev_b32_e32 v8, 2, v5
	v_lshlrev_b32_e32 v9, 1, v5
	v_and_b32_e32 v4, 0xc0, v4
	v_and_or_b32 v7, v5, s1, v7
	v_and_b32_e32 v8, 4, v8
	v_and_b32_e32 v9, 24, v9
	v_sub_u32_e32 v2, v2, v4
	v_or3_b32 v7, v7, v8, v9
	v_lshlrev_b32_e32 v8, 5, v0
	v_ashrrev_i16_sdwa v2, v181, sext(v2) dst_sel:DWORD dst_unused:UNUSED_PAD src0_sel:DWORD src1_sel:BYTE_0
	v_and_b32_e32 v8, 32, v8
	v_bfe_i32 v2, v2, 0, 16
	v_add_lshl_u32 v4, v8, v2, 1
	v_lshl_add_u32 v198, v7, 11, v4
	v_lshl_add_u32 v200, v5, 11, v4
	v_bfe_i32 v4, v6, 27, 1
	v_lshrrev_b32_e32 v4, 22, v4
	v_add_u32_e32 v4, v3, v4
	v_and_b32_e32 v4, 0xfffffc00, v4
	v_sub_u32_e32 v3, v3, v4
	v_lshrrev_b32_e32 v4, 4, v3
	v_bitop3_b32 v5, v4, v3, 32 bitop3:0x6c
	v_ashrrev_i32_e32 v4, 31, v6
	v_lshrrev_b32_e32 v4, 26, v4
	v_ashrrev_i32_e32 v3, 31, v3
	v_add_u32_e32 v4, v6, v4
	v_lshrrev_b32_e32 v3, 26, v3
	v_ashrrev_i32_e32 v4, 6, v4
	v_add_u32_e32 v3, v5, v3
	v_lshlrev_b32_e32 v7, 3, v4
	v_ashrrev_i32_e32 v3, 6, v3
	v_and_b32_e32 v7, -16, v7
	v_add_u32_e32 v7, v3, v7
	v_and_b32_e32 v8, 3, v3
	v_lshrrev_b32_e32 v9, 2, v7
	v_lshlrev_b32_e32 v10, 1, v7
	v_and_or_b32 v8, v7, s1, v8
	v_and_b32_e32 v9, 4, v9
	v_and_b32_e32 v10, 24, v10
	v_or3_b32 v8, v8, v9, v10
	v_mul_i32_i24_e32 v10, 64, v3
	v_sub_u32_e32 v5, v5, v10
	s_ashr_i32 s0, s94, 6
	v_lshlrev_b32_e32 v9, 5, v4
	v_ashrrev_i16_sdwa v5, v181, sext(v5) dst_sel:DWORD dst_unused:UNUSED_PAD src0_sel:DWORD src1_sel:BYTE_0
	s_lshl_b32 s54, s0, 10
	v_and_b32_e32 v9, 32, v9
	v_bfe_i32 v5, v5, 0, 16
	v_add_lshl_u32 v9, v9, v5, 1
	s_add_i32 s55, s54, 0
	v_readlane_b32 s2, v254, 51
	v_lshl_add_u32 v176, v8, 11, v9
	s_add_i32 m0, s55, 0x10000
	v_readlane_b32 s3, v254, 52
	v_lshl_add_u32 v202, v7, 11, v9
	s_add_i32 s56, s55, 0x2000
	s_add_i32 s7, s55, 0x4000
	s_add_i32 s15, s55, 0x6000
	s_load_dword s95, s[74:75], 0x0
	global_load_lds_dwordx4 v176, s[2:3]
	s_add_i32 m0, s55, 0x12000
	s_ashr_i32 s1, s94, 8
	global_load_lds_dwordx4 v198, s[2:3]
	v_readlane_b32 s2, v254, 47
	s_mov_b32 m0, s55
	v_readlane_b32 s3, v254, 48
	s_nop 4
	global_load_lds_dwordx4 v202, s[2:3]
	s_mov_b32 m0, s56
	s_nop 0
	global_load_lds_dwordx4 v200, s[2:3]
	v_readlane_b32 s2, v254, 45
	s_add_i32 m0, s55, 0x14000
	v_readlane_b32 s3, v254, 46
	s_nop 4
	global_load_lds_dwordx4 v176, s[2:3]
	s_add_i32 m0, s55, 0x16000
	s_cmp_lg_u32 s1, 1
	global_load_lds_dwordx4 v198, s[2:3]
	v_readlane_b32 s2, v254, 49
	s_mov_b32 m0, s7
	v_readlane_b32 s3, v254, 50
	s_nop 4
	global_load_lds_dwordx4 v202, s[2:3]
	s_mov_b32 m0, s15
	s_nop 0
	global_load_lds_dwordx4 v200, s[2:3]
	s_cbranch_scc1 .LBB0_161
	s_barrier
	s_setprio 1

.LBB0_279:
	s_andn2_b64 vcc, exec, s[0:1]
	s_cbranch_vccnz .LBB0_22
	v_readlane_b32 s0, v255, 25
	s_cmp_gt_i32 s0, 0
	s_mov_b64 s[0:1], -1
	s_cbranch_scc0 .LBB0_298
	v_readlane_b32 s0, v253, 42
	s_waitcnt lgkmcnt(0)
	v_mov_b32_e32 v1, v179
	v_readlane_b32 s1, v253, 43
	s_andn2_b64 vcc, exec, s[0:1]
	v_readfirstlane_b32 s3, v1
	s_cbranch_vccnz .LBB0_297
	v_lshlrev_b32_e32 v4, 4, v1
	v_add_u32_e32 v2, 0x2000, v4
	v_ashrrev_i32_e32 v0, 31, v2
	v_lshrrev_b32_e32 v0, 22, v0
	v_add_u32_e32 v0, v2, v0
	v_ashrrev_i32_e32 v0, 10, v0
	v_mul_i32_i24_e32 v3, 0x400, v0
	v_sub_u32_e32 v2, v2, v3
	v_lshrrev_b32_e32 v3, 4, v2
	v_bitop3_b32 v3, v3, v2, 32 bitop3:0x6c
	v_ashrrev_i32_e32 v2, 31, v3
	v_lshrrev_b32_e32 v2, 26, v2
	v_add_u32_e32 v5, v3, v2
	v_lshlrev_b32_e32 v6, 3, v0
	v_ashrrev_i32_e32 v2, 6, v5
	v_and_b32_e32 v6, -16, v6
	v_add_u32_e32 v6, v2, v6
	v_and_b32_e32 v7, 3, v2
	s_mov_b32 s1, 0x1fffe0
	s_waitcnt vmcnt(0)
	v_lshrrev_b32_e32 v8, 2, v6
	v_lshlrev_b32_e32 v9, 1, v6
	v_and_b32_e32 v5, 0xc0, v5
	v_and_or_b32 v7, v6, s1, v7
	v_and_b32_e32 v8, 4, v8
	v_and_b32_e32 v9, 24, v9
	v_sub_u32_e32 v3, v3, v5
	v_or3_b32 v7, v7, v8, v9
	v_lshlrev_b32_e32 v8, 5, v0
	v_ashrrev_i16_sdwa v3, v181, sext(v3) dst_sel:DWORD dst_unused:UNUSED_PAD src0_sel:DWORD src1_sel:BYTE_0
	v_and_b32_e32 v8, 32, v8
	v_bfe_i32 v3, v3, 0, 16
	v_add_lshl_u32 v5, v8, v3, 1
	v_lshl_add_u32 v128, v7, 11, v5
	v_lshl_add_u32 v130, v6, 11, v5
	v_bfe_i32 v5, v1, 27, 1
	v_lshrrev_b32_e32 v5, 22, v5
	v_add_u32_e32 v5, v4, v5
	v_and_b32_e32 v5, 0xfffffc00, v5
	v_sub_u32_e32 v4, v4, v5
	v_lshrrev_b32_e32 v5, 4, v4
	v_bitop3_b32 v6, v5, v4, 32 bitop3:0x6c
	v_ashrrev_i32_e32 v5, 31, v1
	v_lshrrev_b32_e32 v5, 26, v5
	v_ashrrev_i32_e32 v4, 31, v4
	v_add_u32_e32 v5, v1, v5
	v_lshrrev_b32_e32 v4, 26, v4
	v_ashrrev_i32_e32 v5, 6, v5
	v_add_u32_e32 v4, v6, v4
	v_lshlrev_b32_e32 v7, 3, v5
	v_ashrrev_i32_e32 v4, 6, v4
	v_and_b32_e32 v7, -16, v7
	v_add_u32_e32 v7, v4, v7
	v_and_b32_e32 v8, 3, v4
	v_lshrrev_b32_e32 v9, 2, v7
	v_lshlrev_b32_e32 v10, 1, v7
	v_and_or_b32 v8, v7, s1, v8
	v_and_b32_e32 v9, 4, v9
	v_and_b32_e32 v10, 24, v10
	v_or3_b32 v8, v8, v9, v10
	v_mul_i32_i24_e32 v10, 64, v4
	v_sub_u32_e32 v6, v6, v10
	s_ashr_i32 s0, s3, 6
	v_lshlrev_b32_e32 v9, 5, v5
	v_ashrrev_i16_sdwa v6, v181, sext(v6) dst_sel:DWORD dst_unused:UNUSED_PAD src0_sel:DWORD src1_sel:BYTE_0
	s_lshl_b32 s6, s0, 10
	v_and_b32_e32 v9, 32, v9
	v_bfe_i32 v6, v6, 0, 16
	v_add_lshl_u32 v9, v9, v6, 1
	s_add_i32 s7, s6, 0
	v_readlane_b32 s20, v254, 23
	v_lshl_add_u32 v176, v8, 11, v9
	s_add_i32 m0, s7, 0x10000
	v_readlane_b32 s21, v254, 24
	v_lshl_add_u32 v132, v7, 11, v9
	s_add_i32 s9, s7, 0x2000
	s_add_i32 s15, s7, 0x4000
	s_add_i32 s34, s7, 0x6000
	s_load_dword s50, s[74:75], 0x0
	global_load_lds_dwordx4 v176, s[20:21]
	s_add_i32 m0, s7, 0x12000
	s_ashr_i32 s1, s3, 8
	global_load_lds_dwordx4 v128, s[20:21]
	v_readlane_b32 s20, v254, 19
	s_mov_b32 m0, s7
	v_readlane_b32 s21, v254, 20
	s_nop 4
	global_load_lds_dwordx4 v132, s[20:21]
	s_mov_b32 m0, s9
	s_nop 0
	global_load_lds_dwordx4 v130, s[20:21]
	v_readlane_b32 s20, v254, 17
	s_add_i32 m0, s7, 0x14000
	v_readlane_b32 s21, v254, 18
	s_nop 4
	global_load_lds_dwordx4 v176, s[20:21]
	s_add_i32 m0, s7, 0x16000
	s_cmp_lg_u32 s1, 1
	global_load_lds_dwordx4 v128, s[20:21]
	v_readlane_b32 s20, v254, 21
	s_mov_b32 m0, s15
	v_readlane_b32 s21, v254, 22
	s_nop 4
	global_load_lds_dwordx4 v132, s[20:21]
	s_mov_b32 m0, s34
	s_nop 0
	global_load_lds_dwordx4 v130, s[20:21]
	s_cbranch_scc1 .LBB0_284
	s_barrier
	s_setprio 1

.LBB0_296:
	v_readlane_b32 s50, v254, 13
	v_readlane_b32 s51, v254, 14
	s_barrier
	s_setprio 0
